# xcdremap kernel plus the same unsigned tile-id remap in the conv in-projection unit decode
# speedup vs baseline: 1.0086x; 1.0086x over previous
;     __host__ __device__ bool next(int i, Unit& u) const {
;         const long L = (long)i * G + c; if (L >= nwg) return false;
;         int wgid = (int)L; { const int q = nwg / NXCD, r = nwg % NXCD, xcd = wgid % NXCD, off = wgid / NXCD; wgid = (xcd < r ? xcd * (q + 1) : r * (q + 1) + (xcd - r) * q) + off; }
;         const int nig = WGM * nN, gid = wgid / nig, fm = gid * WGM, gsz = (nM - fm) < WGM ? (nM - fm) : WGM;
;         u.pm = fm + ((wgid % nig) % gsz); u.pn = (wgid % nig) / gsz; u.sw = 0; return true;
.LBB0_126:
	s_add_i32 s61, s61, 1
	s_mul_i32 s4, s61, s36
	s_mul_hi_u32 s5, s61, s28
	s_add_i32 s5, s5, s4
	s_mul_i32 s4, s61, s28
	s_add_u32 s42, s4, s2
	s_addc_u32 s43, s5, s33
	v_cmp_gt_i64_e32 vcc, s[42:43], v[168:169]
	v_cmp_lt_i64_e64 s[4:5], s[42:43], v[166:167]
	s_cbranch_vccnz .LBB0_128
	s_lshr_b32 s17, s42, 3
	s_and_b32 s16, s42, 7
	s_mulk_i32 s16, 0xc0
	s_add_i32 s16, s16, s17
	s_mul_hi_i32 s17, s16, 0x2aaaaaab
	s_lshr_b32 s18, s17, 31
	s_ashr_i32 s17, s17, 4
	s_add_i32 s17, s17, s18
	s_lshl_b32 s18, s17, 3
	s_mulk_i32 s17, 0x60
	s_sub_i32 s17, s16, s17
	s_lshr_b32 s16, s17, 3
	s_lshl_b32 s19, s16, 3
	s_sub_i32 s17, s17, s19
	s_add_i32 s18, s18, s17
